# ret_out_item output stage: gate and weight loads of blocks 1..11 issued up front into dead registers, counted vmcnt per block (no load or store-ack round trip per 4-column block)
# speedup vs baseline: 1.0023x; 1.0023x over previous
; __device__ __forceinline__ float half_sum(float v) { auto rr = __builtin_amdgcn_permlane32_swap(__float_as_uint(v), __float_as_uint(v), false, false); return __uint_as_float(rr[0]) + __uint_as_float(rr[1]); }
; __device__ __forceinline__ void ret_out_item(LAS unsigned char* lds, const bf16* Z, const bf16* AT, const float* gn, bf16* MIXED, int b, int c, const float* lgs) {
;     ...
;     float s = 0.f;
; #pragma unroll
;     for (int i = 0; i < 4; ++i)
; #pragma unroll
;         for (int r = 0; r < 16; ++r) s += acc[i][r];
;     s = half_sum(s); const float mean = s * (1.f / 128.f); float v = 0.f;
; #pragma unroll
;     for (int i = 0; i < 4; ++i)
; #pragma unroll
;         for (int r = 0; r < 16; ++r) { const float dd = acc[i][r] - mean; v += dd * dd; }
;     v = half_sum(v); const float rstd = rsqrtf(v * (1.f / 128.f) + EPS);
; #pragma unroll
;     for (int eb = 0; eb < 4; ++eb)
; #pragma unroll
;         for (int rg = 0; rg < 4; ++rg) { const int e0 = 32 * eb + 8 * rg + 4 * hi;
;             const u32x2 gt = *(const u32x2*)(Z + (size_t)row * NZ + ZC_RG + hh * 128 + e0); const f32x4 gg = *(const f32x4*)(gn + hh * 128 + e0);
.LBB0_681:
	v_mov_b64_e32 v[66:67], s[4:5]
	v_mad_u64_u32 v[66:67], s[4:5], v142, s74, v[66:67]
	v_lshl_add_u64 v[72:73], v[66:67], 0, s[8:9]
	v_lshl_add_u64 v[74:75], v[72:73], 0, v[138:139]
	global_load_dwordx2 v[76:77], v[74:75], off offset:3904
	s_nop 4
	v_add_f32_e32 v1, 0, v18
	v_add_f32_e32 v1, v19, v1
	v_add_f32_e32 v1, v20, v1
	v_add_f32_e32 v1, v21, v1
	v_add_f32_e32 v1, v22, v1
	v_add_f32_e32 v1, v23, v1
	v_add_f32_e32 v1, v24, v1
	v_add_f32_e32 v1, v25, v1
	v_add_f32_e32 v1, v26, v1
	v_add_f32_e32 v1, v27, v1
	v_add_f32_e32 v1, v28, v1
	v_add_f32_e32 v1, v29, v1
	v_add_f32_e32 v1, v30, v1
	v_add_f32_e32 v1, v31, v1
	v_add_f32_e32 v1, v32, v1
	v_add_f32_e32 v1, v33, v1
	v_add_f32_e32 v1, v2, v1
	v_add_f32_e32 v1, v3, v1
	v_add_f32_e32 v1, v4, v1
	v_add_f32_e32 v1, v5, v1
	v_add_f32_e32 v1, v6, v1
	v_add_f32_e32 v1, v7, v1
	v_add_f32_e32 v1, v8, v1
	v_add_f32_e32 v1, v9, v1
	v_add_f32_e32 v1, v10, v1
	v_add_f32_e32 v1, v11, v1
	v_add_f32_e32 v1, v12, v1
	v_add_f32_e32 v1, v13, v1
	v_add_f32_e32 v1, v14, v1
	v_add_f32_e32 v1, v15, v1
	v_add_f32_e32 v1, v16, v1
	v_add_f32_e32 v1, v17, v1
	v_add_f32_e32 v1, v50, v1
	v_add_f32_e32 v1, v51, v1
	v_add_f32_e32 v1, v52, v1
	v_add_f32_e32 v1, v53, v1
	v_add_f32_e32 v1, v54, v1
	v_add_f32_e32 v1, v55, v1
	v_add_f32_e32 v1, v56, v1
	v_add_f32_e32 v1, v57, v1
	v_add_f32_e32 v1, v58, v1
	v_add_f32_e32 v1, v59, v1
	v_add_f32_e32 v1, v60, v1
	v_add_f32_e32 v1, v61, v1
	v_add_f32_e32 v1, v62, v1
	v_add_f32_e32 v1, v63, v1
	v_add_f32_e32 v1, v64, v1
	v_add_f32_e32 v1, v65, v1
	v_add_f32_e32 v1, v34, v1
	v_add_f32_e32 v1, v35, v1
	v_add_f32_e32 v1, v36, v1
	v_add_f32_e32 v1, v37, v1
	v_add_f32_e32 v1, v38, v1
	v_add_f32_e32 v1, v39, v1
	v_add_f32_e32 v1, v40, v1
	v_add_f32_e32 v1, v41, v1
	v_add_f32_e32 v1, v42, v1
	v_add_f32_e32 v1, v43, v1
	v_add_f32_e32 v1, v44, v1
	v_add_f32_e32 v1, v45, v1
	v_add_f32_e32 v1, v46, v1
	v_add_f32_e32 v1, v47, v1
	v_add_f32_e32 v1, v48, v1
	v_add_f32_e32 v1, v49, v1
	v_mov_b32_e32 v66, v1
	s_lshl_b64 s[4:5], s[6:7], 2
	s_nop 0
	v_permlane32_swap_b32_e32 v1, v66
	v_mov_b32_e32 v143, v0
	s_add_u32 s4, s11, s4
	v_add_f32_e32 v1, v1, v66
	s_addc_u32 s5, s10, s5
	v_lshlrev_b64 v[66:67], 11, v[142:143]
	v_mul_f32_e32 v110, 0x3c000000, v1
	v_lshl_add_u64 v[66:67], s[2:3], 0, v[66:67]
	v_lshl_add_u64 v[70:71], s[4:5], 0, v[140:141]
	v_lshl_add_u64 v[104:105], v[66:67], 0, s[8:9]
	global_load_dwordx4 v[66:69], v[70:71], off
	global_load_dwordx2 v[220:221], v[74:75], off offset:3920
	global_load_dwordx4 v[176:179], v[70:71], off offset:32
	global_load_dwordx2 v[222:223], v[74:75], off offset:3936
	global_load_dwordx4 v[180:183], v[70:71], off offset:64
	global_load_dwordx2 v[224:225], v[74:75], off offset:3952
	global_load_dwordx4 v[184:187], v[70:71], off offset:96
	global_load_dwordx2 v[226:227], v[74:75], off offset:3968
	global_load_dwordx4 v[188:191], v[70:71], off offset:128
	global_load_dwordx2 v[228:229], v[74:75], off offset:3984
	global_load_dwordx4 v[192:195], v[70:71], off offset:160
	global_load_dwordx2 v[230:231], v[74:75], off offset:4000
	global_load_dwordx4 v[196:199], v[70:71], off offset:192
	global_load_dwordx2 v[232:233], v[74:75], off offset:4016
	global_load_dwordx4 v[200:203], v[70:71], off offset:224
	global_load_dwordx2 v[234:235], v[74:75], off offset:4032
	global_load_dwordx4 v[204:207], v[70:71], off offset:256
	global_load_dwordx2 v[236:237], v[74:75], off offset:4048
	global_load_dwordx4 v[208:211], v[70:71], off offset:288
	global_load_dwordx2 v[238:239], v[74:75], off offset:4064
	global_load_dwordx4 v[212:215], v[70:71], off offset:320
	global_load_dwordx2 v[240:241], v[74:75], off offset:4080
	global_load_dwordx4 v[216:219], v[70:71], off offset:352
	v_pk_add_f32 v[106:107], v[18:19], v[110:111] op_sel_hi:[1,0] neg_lo:[0,1] neg_hi:[0,1]
	s_waitcnt vmcnt(22) lgkmcnt(0)
	v_lshlrev_b32_e32 v108, 16, v76
	v_and_b32_e32 v109, 0xffff0000, v76
	v_mul_f32_e32 v1, 0xbfb8aa3b, v108
	v_exp_f32_e32 v1, v1
	v_mul_f32_e32 v19, 0xbfb8aa3b, v109
	v_and_b32_e32 v117, 0xffff0000, v77
	v_pk_add_f32 v[102:103], v[20:21], v[110:111] op_sel_hi:[1,0] neg_lo:[0,1] neg_hi:[0,1]
	v_exp_f32_e32 v20, v19
	v_mul_f32_e32 v21, 0xbfb8aa3b, v117
	v_exp_f32_e32 v21, v21
	v_mul_f32_e32 v18, v107, v107
	v_pk_fma_f32 v[18:19], v[106:107], v[106:107], v[18:19] op_sel_hi:[1,1,0]
	v_add_f32_e32 v1, 1.0, v1
	v_rcp_f32_e32 v114, v1
	v_add_f32_e32 v1, 1.0, v20
	v_pk_fma_f32 v[18:19], v[102:103], v[102:103], v[18:19]
	v_mul_f32_e32 v20, v103, v103
	v_pk_add_f32 v[18:19], v[20:21], v[18:19] op_sel_hi:[0,1]
	v_pk_add_f32 v[112:113], v[22:23], v[110:111] op_sel_hi:[1,0] neg_lo:[0,1] neg_hi:[0,1]
	v_pk_add_f32 v[100:101], v[24:25], v[110:111] op_sel_hi:[1,0] neg_lo:[0,1] neg_hi:[0,1]
	v_pk_fma_f32 v[18:19], v[112:113], v[112:113], v[18:19]
	v_mul_f32_e32 v20, v113, v113
	v_pk_add_f32 v[18:19], v[20:21], v[18:19] op_sel_hi:[0,1]
	v_pk_fma_f32 v[18:19], v[100:101], v[100:101], v[18:19]
	v_mul_f32_e32 v20, v101, v101
	v_pk_add_f32 v[18:19], v[20:21], v[18:19] op_sel_hi:[0,1]
	v_pk_add_f32 v[98:99], v[26:27], v[110:111] op_sel_hi:[1,0] neg_lo:[0,1] neg_hi:[0,1]
	v_pk_add_f32 v[96:97], v[28:29], v[110:111] op_sel_hi:[1,0] neg_lo:[0,1] neg_hi:[0,1]
	v_pk_fma_f32 v[18:19], v[98:99], v[98:99], v[18:19]
	v_mul_f32_e32 v20, v99, v99
	v_pk_add_f32 v[18:19], v[20:21], v[18:19] op_sel_hi:[0,1]
	v_pk_fma_f32 v[18:19], v[96:97], v[96:97], v[18:19]
	v_mul_f32_e32 v20, v97, v97
	v_pk_add_f32 v[18:19], v[20:21], v[18:19] op_sel_hi:[0,1]
	v_pk_add_f32 v[94:95], v[30:31], v[110:111] op_sel_hi:[1,0] neg_lo:[0,1] neg_hi:[0,1]
	v_pk_add_f32 v[92:93], v[32:33], v[110:111] op_sel_hi:[1,0] neg_lo:[0,1] neg_hi:[0,1]
; __device__ __forceinline__ float bflo(unsigned w) { return __uint_as_float(w << 16); }
; __device__ __forceinline__ float bfhi(unsigned w) { return __uint_as_float(w & 0xffff0000u); }
; __device__ __forceinline__ unsigned pk2(float lo, float hi) { const f32x2 v = {lo, hi}; return __builtin_bit_cast(unsigned, __builtin_convertvector(v, bf16x2_t)); }
; __device__ __forceinline__ float half_sum(float v) { auto rr = __builtin_amdgcn_permlane32_swap(__float_as_uint(v), __float_as_uint(v), false, false); return __uint_as_float(rr[0]) + __uint_as_float(rr[1]); }
; __device__ __forceinline__ float silu(float x) { return x * __builtin_amdgcn_rcpf(1.f + __builtin_amdgcn_exp2f(-1.4426950408889634f * x)); }
; __device__ __forceinline__ void ret_out_item(LAS unsigned char* lds, const bf16* Z, const bf16* AT, const float* gn, bf16* MIXED, int b, int c, const float* lgs) {
;     ...
;     s = half_sum(s); const float mean = s * (1.f / 128.f); float v = 0.f;
; #pragma unroll
;     for (int i = 0; i < 4; ++i)
; #pragma unroll
;         for (int r = 0; r < 16; ++r) { const float dd = acc[i][r] - mean; v += dd * dd; }
;     v = half_sum(v); const float rstd = rsqrtf(v * (1.f / 128.f) + EPS);
; #pragma unroll
;     for (int eb = 0; eb < 4; ++eb)
; #pragma unroll
;         for (int rg = 0; rg < 4; ++rg) { const int e0 = 32 * eb + 8 * rg + 4 * hi;
;             const u32x2 gt = *(const u32x2*)(Z + (size_t)row * NZ + ZC_RG + hh * 128 + e0); const f32x4 gg = *(const f32x4*)(gn + hh * 128 + e0);
;             const float y0 = (acc[eb][4 * rg] - mean) * rstd * gg.x * silu(bflo(gt.x)), y1 = (acc[eb][4 * rg + 1] - mean) * rstd * gg.y * silu(bfhi(gt.x));
;             const float y2 = (acc[eb][4 * rg + 2] - mean) * rstd * gg.z * silu(bflo(gt.y)), y3 = (acc[eb][4 * rg + 3] - mean) * rstd * gg.w * silu(bfhi(gt.y));
;             u32x2 w; w.x = pk2(y0, y1); w.y = pk2(y2, y3); *(u32x2*)(MIXED + (size_t)row * 1024 + 512 + hh * 128 + e0) = w; }
	v_pk_fma_f32 v[18:19], v[94:95], v[94:95], v[18:19]
	v_mul_f32_e32 v20, v95, v95
	v_pk_add_f32 v[18:19], v[20:21], v[18:19] op_sel_hi:[0,1]
	v_pk_fma_f32 v[18:19], v[92:93], v[92:93], v[18:19]
	v_mul_f32_e32 v20, v93, v93
	v_pk_add_f32 v[18:19], v[20:21], v[18:19] op_sel_hi:[0,1]
	v_pk_add_f32 v[90:91], v[2:3], v[110:111] op_sel_hi:[1,0] neg_lo:[0,1] neg_hi:[0,1]
	v_pk_add_f32 v[88:89], v[4:5], v[110:111] op_sel_hi:[1,0] neg_lo:[0,1] neg_hi:[0,1]
	v_pk_fma_f32 v[2:3], v[90:91], v[90:91], v[18:19]
	v_mul_f32_e32 v4, v91, v91
	v_pk_add_f32 v[2:3], v[4:5], v[2:3] op_sel_hi:[0,1]
	v_pk_fma_f32 v[2:3], v[88:89], v[88:89], v[2:3]
	v_mul_f32_e32 v4, v89, v89
	v_pk_add_f32 v[2:3], v[4:5], v[2:3] op_sel_hi:[0,1]
	v_pk_add_f32 v[86:87], v[6:7], v[110:111] op_sel_hi:[1,0] neg_lo:[0,1] neg_hi:[0,1]
	v_pk_add_f32 v[84:85], v[8:9], v[110:111] op_sel_hi:[1,0] neg_lo:[0,1] neg_hi:[0,1]
	v_pk_fma_f32 v[2:3], v[86:87], v[86:87], v[2:3]
	v_mul_f32_e32 v4, v87, v87
	v_pk_add_f32 v[2:3], v[4:5], v[2:3] op_sel_hi:[0,1]
	v_pk_fma_f32 v[2:3], v[84:85], v[84:85], v[2:3]
	v_mul_f32_e32 v4, v85, v85
	v_pk_add_f32 v[2:3], v[4:5], v[2:3] op_sel_hi:[0,1]
	v_pk_add_f32 v[82:83], v[10:11], v[110:111] op_sel_hi:[1,0] neg_lo:[0,1] neg_hi:[0,1]
	v_pk_add_f32 v[80:81], v[12:13], v[110:111] op_sel_hi:[1,0] neg_lo:[0,1] neg_hi:[0,1]
	v_pk_fma_f32 v[2:3], v[82:83], v[82:83], v[2:3]
	v_mul_f32_e32 v4, v83, v83
	v_pk_add_f32 v[2:3], v[4:5], v[2:3] op_sel_hi:[0,1]
	v_pk_fma_f32 v[2:3], v[80:81], v[80:81], v[2:3]
	v_mul_f32_e32 v4, v81, v81
	v_pk_add_f32 v[2:3], v[4:5], v[2:3] op_sel_hi:[0,1]
	v_pk_add_f32 v[78:79], v[14:15], v[110:111] op_sel_hi:[1,0] neg_lo:[0,1] neg_hi:[0,1]
	v_lshlrev_b32_e32 v116, 16, v77
	v_pk_fma_f32 v[2:3], v[78:79], v[78:79], v[2:3]
	v_mul_f32_e32 v4, v79, v79
	v_pk_add_f32 v[76:77], v[16:17], v[110:111] op_sel_hi:[1,0] neg_lo:[0,1] neg_hi:[0,1]
	v_pk_add_f32 v[2:3], v[4:5], v[2:3] op_sel_hi:[0,1]
	v_pk_fma_f32 v[2:3], v[76:77], v[76:77], v[2:3]
	v_mul_f32_e32 v4, v77, v77
	v_pk_add_f32 v[2:3], v[4:5], v[2:3] op_sel_hi:[0,1]
	v_pk_add_f32 v[50:51], v[50:51], v[110:111] op_sel_hi:[1,0] neg_lo:[0,1] neg_hi:[0,1]
	v_pk_add_f32 v[32:33], v[52:53], v[110:111] op_sel_hi:[1,0] neg_lo:[0,1] neg_hi:[0,1]
	v_pk_fma_f32 v[2:3], v[50:51], v[50:51], v[2:3]
	v_mul_f32_e32 v4, v51, v51
	v_pk_add_f32 v[2:3], v[4:5], v[2:3] op_sel_hi:[0,1]
	v_pk_fma_f32 v[2:3], v[32:33], v[32:33], v[2:3]
	v_mul_f32_e32 v4, v33, v33
	v_pk_add_f32 v[2:3], v[4:5], v[2:3] op_sel_hi:[0,1]
	v_pk_add_f32 v[30:31], v[54:55], v[110:111] op_sel_hi:[1,0] neg_lo:[0,1] neg_hi:[0,1]
	v_pk_add_f32 v[28:29], v[56:57], v[110:111] op_sel_hi:[1,0] neg_lo:[0,1] neg_hi:[0,1]
	v_pk_fma_f32 v[2:3], v[30:31], v[30:31], v[2:3]
	v_mul_f32_e32 v4, v31, v31
	v_pk_add_f32 v[2:3], v[4:5], v[2:3] op_sel_hi:[0,1]
	v_pk_fma_f32 v[2:3], v[28:29], v[28:29], v[2:3]
	v_mul_f32_e32 v4, v29, v29
	v_rcp_f32_e32 v115, v1
	v_mul_f32_e32 v1, 0xbfb8aa3b, v116
	v_pk_add_f32 v[2:3], v[4:5], v[2:3] op_sel_hi:[0,1]
	v_pk_add_f32 v[26:27], v[58:59], v[110:111] op_sel_hi:[1,0] neg_lo:[0,1] neg_hi:[0,1]
	v_exp_f32_e32 v1, v1
	v_pk_fma_f32 v[2:3], v[26:27], v[26:27], v[2:3]
	v_mul_f32_e32 v4, v27, v27
	v_pk_add_f32 v[24:25], v[60:61], v[110:111] op_sel_hi:[1,0] neg_lo:[0,1] neg_hi:[0,1]
	v_pk_add_f32 v[2:3], v[4:5], v[2:3] op_sel_hi:[0,1]
	v_pk_fma_f32 v[2:3], v[24:25], v[24:25], v[2:3]
	v_mul_f32_e32 v4, v25, v25
	v_pk_add_f32 v[2:3], v[4:5], v[2:3] op_sel_hi:[0,1]
	v_pk_add_f32 v[22:23], v[62:63], v[110:111] op_sel_hi:[1,0] neg_lo:[0,1] neg_hi:[0,1]
	v_add_f32_e32 v1, 1.0, v1
	v_pk_fma_f32 v[2:3], v[22:23], v[22:23], v[2:3]
	v_mul_f32_e32 v4, v23, v23
	v_rcp_f32_e32 v118, v1
	v_add_f32_e32 v1, 1.0, v21
	v_pk_add_f32 v[20:21], v[64:65], v[110:111] op_sel_hi:[1,0] neg_lo:[0,1] neg_hi:[0,1]
	v_pk_add_f32 v[2:3], v[4:5], v[2:3] op_sel_hi:[0,1]
	v_pk_fma_f32 v[2:3], v[20:21], v[20:21], v[2:3]
	v_mul_f32_e32 v4, v21, v21
	v_pk_add_f32 v[2:3], v[4:5], v[2:3] op_sel_hi:[0,1]
	v_pk_add_f32 v[18:19], v[34:35], v[110:111] op_sel_hi:[1,0] neg_lo:[0,1] neg_hi:[0,1]
	v_pk_add_f32 v[16:17], v[36:37], v[110:111] op_sel_hi:[1,0] neg_lo:[0,1] neg_hi:[0,1]
	v_pk_fma_f32 v[2:3], v[18:19], v[18:19], v[2:3]
	v_mul_f32_e32 v4, v19, v19
	v_pk_add_f32 v[2:3], v[4:5], v[2:3] op_sel_hi:[0,1]
	v_pk_fma_f32 v[2:3], v[16:17], v[16:17], v[2:3]
	v_mul_f32_e32 v4, v17, v17
	v_pk_add_f32 v[2:3], v[4:5], v[2:3] op_sel_hi:[0,1]
	v_pk_add_f32 v[14:15], v[38:39], v[110:111] op_sel_hi:[1,0] neg_lo:[0,1] neg_hi:[0,1]
	v_pk_add_f32 v[12:13], v[40:41], v[110:111] op_sel_hi:[1,0] neg_lo:[0,1] neg_hi:[0,1]
	v_pk_fma_f32 v[2:3], v[14:15], v[14:15], v[2:3]
	v_mul_f32_e32 v4, v15, v15
	v_pk_add_f32 v[2:3], v[4:5], v[2:3] op_sel_hi:[0,1]
	v_pk_fma_f32 v[2:3], v[12:13], v[12:13], v[2:3]
	v_mul_f32_e32 v4, v13, v13
	v_pk_add_f32 v[2:3], v[4:5], v[2:3] op_sel_hi:[0,1]
	v_pk_add_f32 v[10:11], v[42:43], v[110:111] op_sel_hi:[1,0] neg_lo:[0,1] neg_hi:[0,1]
	v_pk_add_f32 v[8:9], v[44:45], v[110:111] op_sel_hi:[1,0] neg_lo:[0,1] neg_hi:[0,1]
	v_pk_fma_f32 v[2:3], v[10:11], v[10:11], v[2:3]
	v_mul_f32_e32 v4, v11, v11
	v_pk_add_f32 v[2:3], v[4:5], v[2:3] op_sel_hi:[0,1]
	v_pk_fma_f32 v[2:3], v[8:9], v[8:9], v[2:3]
	v_mul_f32_e32 v4, v9, v9
	v_pk_add_f32 v[2:3], v[4:5], v[2:3] op_sel_hi:[0,1]
	v_pk_add_f32 v[4:5], v[46:47], v[110:111] op_sel_hi:[1,0] neg_lo:[0,1] neg_hi:[0,1]
	v_pk_add_f32 v[48:49], v[48:49], v[110:111] op_sel_hi:[1,0] neg_lo:[0,1] neg_hi:[0,1]
	v_pk_fma_f32 v[2:3], v[4:5], v[4:5], v[2:3]
	v_mul_f32_e32 v6, v5, v5
	v_pk_add_f32 v[2:3], v[6:7], v[2:3] op_sel_hi:[0,1]
	v_pk_fma_f32 v[2:3], v[48:49], v[48:49], v[2:3]
	v_mul_f32_e32 v6, v49, v49
	v_pk_add_f32 v[2:3], v[6:7], v[2:3] op_sel_hi:[0,1]
	v_rcp_f32_e32 v119, v1
	v_mov_b32_e32 v1, v2
	s_nop 1
	v_permlane32_swap_b32_e32 v2, v1
	v_add_f32_e32 v1, v2, v1
	v_fmamk_f32 v1, v1, 0x3c000000, v152
	v_mul_f32_e32 v2, 0x4b800000, v1
	v_cmp_gt_f32_e32 vcc, s66, v1
	v_pk_mul_f32 v[34:35], v[118:119], v[116:117]
	v_lshl_add_u64 v[38:39], v[104:105], 0, v[138:139]
	v_cndmask_b32_e32 v1, v1, v2, vcc
	v_rsq_f32_e32 v1, v1
	v_pk_mul_f32 v[2:3], v[114:115], v[108:109]
	s_mov_b32 s2, 0x2600000
	v_mul_f32_e32 v6, 0x45800000, v1
	v_cndmask_b32_e32 v6, v1, v6, vcc
	v_pk_mul_f32 v[36:37], v[106:107], v[6:7] op_sel_hi:[1,0]
	s_nop 0
	v_pk_mul_f32 v[36:37], v[66:67], v[36:37]
	s_nop 0
	v_pk_mul_f32 v[2:3], v[2:3], v[36:37]
	v_pk_mul_f32 v[36:37], v[102:103], v[6:7] op_sel_hi:[1,0]
	v_cvt_pk_bf16_f32 v2, v2, v3
	v_pk_mul_f32 v[36:37], v[68:69], v[36:37]
	s_nop 0
	v_pk_mul_f32 v[34:35], v[34:35], v[36:37]
	s_nop 0
	v_cvt_pk_bf16_f32 v3, v34, v35
	v_add_co_u32_e32 v34, vcc, s2, v38
	s_mov_b64 s[2:3], 0x2600400
	s_nop 0
	v_addc_co_u32_e32 v35, vcc, 0, v39, vcc
	global_store_dwordx2 v[34:35], v[2:3], off offset:1024
	s_waitcnt vmcnt(21)
; __device__ __forceinline__ float bflo(unsigned w) { return __uint_as_float(w << 16); }
; __device__ __forceinline__ float bfhi(unsigned w) { return __uint_as_float(w & 0xffff0000u); }
; __device__ __forceinline__ unsigned pk2(float lo, float hi) { const f32x2 v = {lo, hi}; return __builtin_bit_cast(unsigned, __builtin_convertvector(v, bf16x2_t)); }
; __device__ __forceinline__ float silu(float x) { return x * __builtin_amdgcn_rcpf(1.f + __builtin_amdgcn_exp2f(-1.4426950408889634f * x)); }
; __device__ __forceinline__ void ret_out_item(LAS unsigned char* lds, const bf16* Z, const bf16* AT, const float* gn, bf16* MIXED, int b, int c, const float* lgs) {
;     ...
; #pragma unroll
;     for (int eb = 0; eb < 4; ++eb)
; #pragma unroll
;         for (int rg = 0; rg < 4; ++rg) { const int e0 = 32 * eb + 8 * rg + 4 * hi;
;             const u32x2 gt = *(const u32x2*)(Z + (size_t)row * NZ + ZC_RG + hh * 128 + e0); const f32x4 gg = *(const f32x4*)(gn + hh * 128 + e0);
;             const float y0 = (acc[eb][4 * rg] - mean) * rstd * gg.x * silu(bflo(gt.x)), y1 = (acc[eb][4 * rg + 1] - mean) * rstd * gg.y * silu(bfhi(gt.x));
;             const float y2 = (acc[eb][4 * rg + 2] - mean) * rstd * gg.z * silu(bflo(gt.y)), y3 = (acc[eb][4 * rg + 3] - mean) * rstd * gg.w * silu(bfhi(gt.y));
;             u32x2 w; w.x = pk2(y0, y1); w.y = pk2(y2, y3); *(u32x2*)(MIXED + (size_t)row * 1024 + 512 + hh * 128 + e0) = w; }
	v_mov_b32_e32 v40, v220
	v_mov_b32_e32 v41, v221
	v_mov_b32_e32 v34, v176
	v_mov_b32_e32 v35, v177
	v_mov_b32_e32 v36, v178
	v_mov_b32_e32 v37, v179
	s_nop 0
	v_lshl_add_u64 v[2:3], v[38:39], 0, s[2:3]
	s_mov_b64 s[2:3], 0xf40
	s_waitcnt lgkmcnt(0)
	v_lshlrev_b32_e32 v42, 16, v40
	v_mul_f32_e32 v1, 0xbfb8aa3b, v42
	v_and_b32_e32 v43, 0xffff0000, v40
	v_exp_f32_e32 v1, v1
	v_mul_f32_e32 v7, 0xbfb8aa3b, v43
	v_exp_f32_e32 v7, v7
	v_lshlrev_b32_e32 v40, 16, v41
	v_add_f32_e32 v1, 1.0, v1
	v_rcp_f32_e32 v38, v1
	v_add_f32_e32 v1, 1.0, v7
	v_rcp_f32_e32 v39, v1
	v_and_b32_e32 v41, 0xffff0000, v41
	v_mul_f32_e32 v1, 0xbfb8aa3b, v40
	v_pk_mul_f32 v[44:45], v[112:113], v[6:7] op_sel_hi:[1,0]
	v_exp_f32_e32 v1, v1
	v_mul_f32_e32 v7, 0xbfb8aa3b, v41
	v_exp_f32_e32 v7, v7
	v_pk_mul_f32 v[38:39], v[38:39], v[42:43]
	v_add_f32_e32 v1, 1.0, v1
	v_rcp_f32_e32 v42, v1
	v_add_f32_e32 v1, 1.0, v7
	v_rcp_f32_e32 v43, v1
	v_pk_mul_f32 v[34:35], v[34:35], v[44:45]
	s_nop 0
	v_pk_mul_f32 v[34:35], v[34:35], v[38:39]
	v_pk_mul_f32 v[38:39], v[100:101], v[6:7] op_sel_hi:[1,0]
	v_cvt_pk_bf16_f32 v34, v34, v35
	v_pk_mul_f32 v[36:37], v[36:37], v[38:39]
	v_pk_mul_f32 v[38:39], v[42:43], v[40:41]
	v_pk_mul_f32 v[40:41], v[98:99], v[6:7] op_sel_hi:[1,0]
	v_pk_mul_f32 v[36:37], v[36:37], v[38:39]
	v_pk_mul_f32 v[42:43], v[96:97], v[6:7] op_sel_hi:[1,0]
	v_cvt_pk_bf16_f32 v35, v36, v37
	global_store_dwordx2 v[2:3], v[34:35], off offset:16
	s_waitcnt vmcnt(20)
	v_mov_b32_e32 v38, v222
	v_mov_b32_e32 v39, v223
	v_mov_b32_e32 v34, v180
	v_mov_b32_e32 v35, v181
	v_mov_b32_e32 v36, v182
	v_mov_b32_e32 v37, v183
	s_nop 0
	s_waitcnt lgkmcnt(0)
	v_lshlrev_b32_e32 v44, 16, v38
	v_and_b32_e32 v45, 0xffff0000, v38
	v_lshlrev_b32_e32 v38, 16, v39
	v_and_b32_e32 v39, 0xffff0000, v39
	v_mul_f32_e32 v1, 0xbfb8aa3b, v44
	v_mul_f32_e32 v7, 0xbfb8aa3b, v45
	v_mul_f32_e32 v46, 0xbfb8aa3b, v38
	v_mul_f32_e32 v47, 0xbfb8aa3b, v39
	v_exp_f32_e32 v1, v1
	v_exp_f32_e32 v7, v7
	v_exp_f32_e32 v46, v46
	v_exp_f32_e32 v47, v47
	v_add_f32_e32 v1, 1.0, v1
	v_add_f32_e32 v7, 1.0, v7
	v_add_f32_e32 v52, 1.0, v46
	v_add_f32_e32 v53, 1.0, v47
	v_rcp_f32_e32 v46, v1
	v_rcp_f32_e32 v47, v7
	v_rcp_f32_e32 v52, v52
	v_rcp_f32_e32 v53, v53
	v_pk_mul_f32 v[34:35], v[34:35], v[40:41]
	v_pk_mul_f32 v[36:37], v[36:37], v[42:43]
	v_pk_mul_f32 v[40:41], v[46:47], v[44:45]
	v_pk_mul_f32 v[38:39], v[52:53], v[38:39]
	v_pk_mul_f32 v[34:35], v[34:35], v[40:41]
	v_pk_mul_f32 v[36:37], v[36:37], v[38:39]
	v_cvt_pk_bf16_f32 v34, v34, v35
	v_cvt_pk_bf16_f32 v35, v36, v37
	global_store_dwordx2 v[2:3], v[34:35], off offset:32
	s_waitcnt vmcnt(19)
	v_mov_b32_e32 v38, v224
	v_mov_b32_e32 v39, v225
	v_mov_b32_e32 v34, v184
	v_mov_b32_e32 v35, v185
	v_mov_b32_e32 v36, v186
	v_mov_b32_e32 v37, v187
	s_nop 0
	v_pk_mul_f32 v[40:41], v[94:95], v[6:7] op_sel_hi:[1,0]
	v_pk_mul_f32 v[42:43], v[92:93], v[6:7] op_sel_hi:[1,0]
	s_waitcnt lgkmcnt(0)
	v_lshlrev_b32_e32 v44, 16, v38
	v_and_b32_e32 v45, 0xffff0000, v38
	v_lshlrev_b32_e32 v38, 16, v39
	v_and_b32_e32 v39, 0xffff0000, v39
	v_mul_f32_e32 v1, 0xbfb8aa3b, v44
	v_mul_f32_e32 v7, 0xbfb8aa3b, v45
	v_mul_f32_e32 v46, 0xbfb8aa3b, v38
	v_mul_f32_e32 v47, 0xbfb8aa3b, v39
	v_exp_f32_e32 v1, v1
	v_exp_f32_e32 v7, v7
	v_exp_f32_e32 v46, v46
	v_exp_f32_e32 v47, v47
	v_add_f32_e32 v1, 1.0, v1
	v_add_f32_e32 v7, 1.0, v7
	v_add_f32_e32 v52, 1.0, v46
	v_add_f32_e32 v53, 1.0, v47
	v_rcp_f32_e32 v46, v1
	v_rcp_f32_e32 v47, v7
	v_rcp_f32_e32 v52, v52
	v_rcp_f32_e32 v53, v53
	v_pk_mul_f32 v[34:35], v[40:41], v[34:35]
	v_pk_mul_f32 v[36:37], v[42:43], v[36:37]
	v_pk_mul_f32 v[40:41], v[46:47], v[44:45]
	v_pk_mul_f32 v[38:39], v[52:53], v[38:39]
	v_pk_mul_f32 v[34:35], v[34:35], v[40:41]
	v_pk_mul_f32 v[36:37], v[36:37], v[38:39]
	v_cvt_pk_bf16_f32 v34, v34, v35
	v_cvt_pk_bf16_f32 v35, v36, v37
	global_store_dwordx2 v[2:3], v[34:35], off offset:48
	s_waitcnt vmcnt(18)
	v_mov_b32_e32 v38, v226
	v_mov_b32_e32 v39, v227
	v_mov_b32_e32 v34, v188
	v_mov_b32_e32 v35, v189
	v_mov_b32_e32 v36, v190
	v_mov_b32_e32 v37, v191
	s_nop 0
	v_pk_mul_f32 v[40:41], v[90:91], v[6:7] op_sel_hi:[1,0]
	v_pk_mul_f32 v[42:43], v[88:89], v[6:7] op_sel_hi:[1,0]
	s_waitcnt lgkmcnt(0)
	v_lshlrev_b32_e32 v44, 16, v38
	v_and_b32_e32 v45, 0xffff0000, v38
	v_lshlrev_b32_e32 v38, 16, v39
	v_and_b32_e32 v39, 0xffff0000, v39
	v_mul_f32_e32 v1, 0xbfb8aa3b, v44
	v_mul_f32_e32 v7, 0xbfb8aa3b, v45
	v_mul_f32_e32 v46, 0xbfb8aa3b, v38
	v_mul_f32_e32 v47, 0xbfb8aa3b, v39
	v_exp_f32_e32 v1, v1
	v_exp_f32_e32 v7, v7
	v_exp_f32_e32 v46, v46
	v_exp_f32_e32 v47, v47
	v_add_f32_e32 v1, 1.0, v1
	v_add_f32_e32 v7, 1.0, v7
	v_add_f32_e32 v52, 1.0, v46
	v_add_f32_e32 v53, 1.0, v47
	v_rcp_f32_e32 v46, v1
	v_rcp_f32_e32 v47, v7
	v_rcp_f32_e32 v52, v52
	v_rcp_f32_e32 v53, v53
	v_pk_mul_f32 v[34:35], v[40:41], v[34:35]
	v_pk_mul_f32 v[36:37], v[42:43], v[36:37]
	v_pk_mul_f32 v[40:41], v[46:47], v[44:45]
	v_pk_mul_f32 v[38:39], v[52:53], v[38:39]
	v_pk_mul_f32 v[34:35], v[34:35], v[40:41]
	v_pk_mul_f32 v[36:37], v[36:37], v[38:39]
	v_cvt_pk_bf16_f32 v34, v34, v35
	v_cvt_pk_bf16_f32 v35, v36, v37
	global_store_dwordx2 v[2:3], v[34:35], off offset:64
	s_waitcnt vmcnt(17)
	v_mov_b32_e32 v38, v228
	v_mov_b32_e32 v39, v229
	v_mov_b32_e32 v34, v192
	v_mov_b32_e32 v35, v193
	v_mov_b32_e32 v36, v194
	v_mov_b32_e32 v37, v195
	s_nop 0
	v_pk_mul_f32 v[40:41], v[86:87], v[6:7] op_sel_hi:[1,0]
	v_pk_mul_f32 v[42:43], v[84:85], v[6:7] op_sel_hi:[1,0]
	s_waitcnt lgkmcnt(0)
; __device__ __forceinline__ float bflo(unsigned w) { return __uint_as_float(w << 16); }
; __device__ __forceinline__ float bfhi(unsigned w) { return __uint_as_float(w & 0xffff0000u); }
; __device__ __forceinline__ unsigned pk2(float lo, float hi) { const f32x2 v = {lo, hi}; return __builtin_bit_cast(unsigned, __builtin_convertvector(v, bf16x2_t)); }
; __device__ __forceinline__ float silu(float x) { return x * __builtin_amdgcn_rcpf(1.f + __builtin_amdgcn_exp2f(-1.4426950408889634f * x)); }
; __device__ __forceinline__ void ret_out_item(LAS unsigned char* lds, const bf16* Z, const bf16* AT, const float* gn, bf16* MIXED, int b, int c, const float* lgs) {
;     ...
; #pragma unroll
;     for (int eb = 0; eb < 4; ++eb)
; #pragma unroll
;         for (int rg = 0; rg < 4; ++rg) { const int e0 = 32 * eb + 8 * rg + 4 * hi;
;             const u32x2 gt = *(const u32x2*)(Z + (size_t)row * NZ + ZC_RG + hh * 128 + e0); const f32x4 gg = *(const f32x4*)(gn + hh * 128 + e0);
;             const float y0 = (acc[eb][4 * rg] - mean) * rstd * gg.x * silu(bflo(gt.x)), y1 = (acc[eb][4 * rg + 1] - mean) * rstd * gg.y * silu(bfhi(gt.x));
;             const float y2 = (acc[eb][4 * rg + 2] - mean) * rstd * gg.z * silu(bflo(gt.y)), y3 = (acc[eb][4 * rg + 3] - mean) * rstd * gg.w * silu(bfhi(gt.y));
;             u32x2 w; w.x = pk2(y0, y1); w.y = pk2(y2, y3); *(u32x2*)(MIXED + (size_t)row * 1024 + 512 + hh * 128 + e0) = w; }
	v_lshlrev_b32_e32 v44, 16, v38
	v_and_b32_e32 v45, 0xffff0000, v38
	v_lshlrev_b32_e32 v38, 16, v39
	v_and_b32_e32 v39, 0xffff0000, v39
	v_mul_f32_e32 v1, 0xbfb8aa3b, v44
	v_mul_f32_e32 v7, 0xbfb8aa3b, v45
	v_mul_f32_e32 v46, 0xbfb8aa3b, v38
	v_mul_f32_e32 v47, 0xbfb8aa3b, v39
	v_exp_f32_e32 v1, v1
	v_exp_f32_e32 v7, v7
	v_exp_f32_e32 v46, v46
	v_exp_f32_e32 v47, v47
	v_add_f32_e32 v1, 1.0, v1
	v_add_f32_e32 v7, 1.0, v7
	v_add_f32_e32 v52, 1.0, v46
	v_add_f32_e32 v53, 1.0, v47
	v_rcp_f32_e32 v46, v1
	v_rcp_f32_e32 v47, v7
	v_rcp_f32_e32 v52, v52
	v_rcp_f32_e32 v53, v53
	v_pk_mul_f32 v[34:35], v[40:41], v[34:35]
	v_pk_mul_f32 v[36:37], v[42:43], v[36:37]
	v_pk_mul_f32 v[40:41], v[46:47], v[44:45]
	v_pk_mul_f32 v[38:39], v[52:53], v[38:39]
	v_pk_mul_f32 v[34:35], v[34:35], v[40:41]
	v_pk_mul_f32 v[36:37], v[36:37], v[38:39]
	v_cvt_pk_bf16_f32 v34, v34, v35
	v_cvt_pk_bf16_f32 v35, v36, v37
	global_store_dwordx2 v[2:3], v[34:35], off offset:80
	s_waitcnt vmcnt(16)
	v_mov_b32_e32 v38, v230
	v_mov_b32_e32 v39, v231
	v_mov_b32_e32 v34, v196
	v_mov_b32_e32 v35, v197
	v_mov_b32_e32 v36, v198
	v_mov_b32_e32 v37, v199
	s_nop 0
	v_pk_mul_f32 v[40:41], v[82:83], v[6:7] op_sel_hi:[1,0]
	v_pk_mul_f32 v[42:43], v[80:81], v[6:7] op_sel_hi:[1,0]
	s_waitcnt lgkmcnt(0)
	v_lshlrev_b32_e32 v44, 16, v38
	v_and_b32_e32 v45, 0xffff0000, v38
	v_lshlrev_b32_e32 v38, 16, v39
	v_and_b32_e32 v39, 0xffff0000, v39
	v_mul_f32_e32 v1, 0xbfb8aa3b, v44
	v_mul_f32_e32 v7, 0xbfb8aa3b, v45
	v_mul_f32_e32 v46, 0xbfb8aa3b, v38
	v_mul_f32_e32 v47, 0xbfb8aa3b, v39
	v_exp_f32_e32 v1, v1
	v_exp_f32_e32 v7, v7
	v_exp_f32_e32 v46, v46
	v_exp_f32_e32 v47, v47
	v_add_f32_e32 v1, 1.0, v1
	v_add_f32_e32 v7, 1.0, v7
	v_add_f32_e32 v52, 1.0, v46
	v_add_f32_e32 v53, 1.0, v47
	v_rcp_f32_e32 v46, v1
	v_rcp_f32_e32 v47, v7
	v_rcp_f32_e32 v52, v52
	v_rcp_f32_e32 v53, v53
	v_pk_mul_f32 v[34:35], v[40:41], v[34:35]
	v_pk_mul_f32 v[36:37], v[42:43], v[36:37]
	v_pk_mul_f32 v[40:41], v[46:47], v[44:45]
	v_pk_mul_f32 v[38:39], v[52:53], v[38:39]
	v_pk_mul_f32 v[34:35], v[34:35], v[40:41]
	v_pk_mul_f32 v[36:37], v[36:37], v[38:39]
	v_cvt_pk_bf16_f32 v34, v34, v35
	v_cvt_pk_bf16_f32 v35, v36, v37
	global_store_dwordx2 v[2:3], v[34:35], off offset:96
	s_waitcnt vmcnt(15)
	v_mov_b32_e32 v38, v232
	v_mov_b32_e32 v39, v233
	v_mov_b32_e32 v34, v200
	v_mov_b32_e32 v35, v201
	v_mov_b32_e32 v36, v202
	v_mov_b32_e32 v37, v203
	s_nop 0
	v_pk_mul_f32 v[40:41], v[78:79], v[6:7] op_sel_hi:[1,0]
	v_pk_mul_f32 v[42:43], v[76:77], v[6:7] op_sel_hi:[1,0]
	s_waitcnt lgkmcnt(0)
	v_lshlrev_b32_e32 v44, 16, v38
	v_and_b32_e32 v45, 0xffff0000, v38
	v_lshlrev_b32_e32 v38, 16, v39
	v_and_b32_e32 v39, 0xffff0000, v39
	v_mul_f32_e32 v1, 0xbfb8aa3b, v44
	v_mul_f32_e32 v7, 0xbfb8aa3b, v45
	v_mul_f32_e32 v46, 0xbfb8aa3b, v38
	v_mul_f32_e32 v47, 0xbfb8aa3b, v39
	v_exp_f32_e32 v1, v1
	v_exp_f32_e32 v7, v7
	v_exp_f32_e32 v46, v46
	v_exp_f32_e32 v47, v47
	v_add_f32_e32 v1, 1.0, v1
	v_add_f32_e32 v7, 1.0, v7
	v_add_f32_e32 v52, 1.0, v46
	v_add_f32_e32 v53, 1.0, v47
	v_rcp_f32_e32 v46, v1
	v_rcp_f32_e32 v47, v7
	v_rcp_f32_e32 v52, v52
	v_rcp_f32_e32 v53, v53
	v_pk_mul_f32 v[34:35], v[40:41], v[34:35]
	v_pk_mul_f32 v[36:37], v[42:43], v[36:37]
	v_pk_mul_f32 v[40:41], v[46:47], v[44:45]
	v_pk_mul_f32 v[38:39], v[52:53], v[38:39]
	v_pk_mul_f32 v[34:35], v[34:35], v[40:41]
	v_pk_mul_f32 v[36:37], v[36:37], v[38:39]
	v_cvt_pk_bf16_f32 v34, v34, v35
	v_cvt_pk_bf16_f32 v35, v36, v37
	global_store_dwordx2 v[2:3], v[34:35], off offset:112
	s_waitcnt vmcnt(14)
	v_mov_b32_e32 v38, v234
	v_mov_b32_e32 v39, v235
	v_mov_b32_e32 v34, v204
	v_mov_b32_e32 v35, v205
	v_mov_b32_e32 v36, v206
	v_mov_b32_e32 v37, v207
	s_nop 0
	v_pk_mul_f32 v[40:41], v[50:51], v[6:7] op_sel_hi:[1,0]
	v_pk_mul_f32 v[32:33], v[32:33], v[6:7] op_sel_hi:[1,0]
	s_waitcnt lgkmcnt(0)
	v_lshlrev_b32_e32 v42, 16, v38
	v_and_b32_e32 v43, 0xffff0000, v38
	v_lshlrev_b32_e32 v38, 16, v39
	v_and_b32_e32 v39, 0xffff0000, v39
	v_mul_f32_e32 v1, 0xbfb8aa3b, v42
	v_mul_f32_e32 v7, 0xbfb8aa3b, v43
	v_mul_f32_e32 v44, 0xbfb8aa3b, v38
	v_mul_f32_e32 v45, 0xbfb8aa3b, v39
	v_exp_f32_e32 v1, v1
	v_exp_f32_e32 v7, v7
	v_exp_f32_e32 v44, v44
	v_exp_f32_e32 v45, v45
	v_add_f32_e32 v1, 1.0, v1
	v_add_f32_e32 v7, 1.0, v7
	v_add_f32_e32 v46, 1.0, v44
	v_add_f32_e32 v47, 1.0, v45
	v_rcp_f32_e32 v44, v1
	v_rcp_f32_e32 v45, v7
	v_rcp_f32_e32 v46, v46
	v_rcp_f32_e32 v47, v47
	v_pk_mul_f32 v[34:35], v[40:41], v[34:35]
	v_pk_mul_f32 v[32:33], v[32:33], v[36:37]
	v_pk_mul_f32 v[36:37], v[44:45], v[42:43]
	v_pk_mul_f32 v[38:39], v[46:47], v[38:39]
	v_pk_mul_f32 v[34:35], v[34:35], v[36:37]
	v_pk_mul_f32 v[32:33], v[32:33], v[38:39]
	v_cvt_pk_bf16_f32 v34, v34, v35
	v_cvt_pk_bf16_f32 v35, v32, v33
	global_store_dwordx2 v[2:3], v[34:35], off offset:128
	s_waitcnt vmcnt(13)
	v_mov_b32_e32 v36, v236
	v_mov_b32_e32 v37, v237
	v_mov_b32_e32 v32, v208
	v_mov_b32_e32 v33, v209
	v_mov_b32_e32 v34, v210
	v_mov_b32_e32 v35, v211
	s_nop 0
	v_pk_mul_f32 v[30:31], v[30:31], v[6:7] op_sel_hi:[1,0]
	v_pk_mul_f32 v[28:29], v[28:29], v[6:7] op_sel_hi:[1,0]
	s_waitcnt lgkmcnt(0)
	v_lshlrev_b32_e32 v38, 16, v36
	v_and_b32_e32 v39, 0xffff0000, v36
	v_lshlrev_b32_e32 v36, 16, v37
	v_and_b32_e32 v37, 0xffff0000, v37
	v_mul_f32_e32 v1, 0xbfb8aa3b, v38
	v_mul_f32_e32 v7, 0xbfb8aa3b, v39
	v_mul_f32_e32 v40, 0xbfb8aa3b, v36
	v_mul_f32_e32 v41, 0xbfb8aa3b, v37
	v_exp_f32_e32 v1, v1
	v_exp_f32_e32 v7, v7
	v_exp_f32_e32 v40, v40
	v_exp_f32_e32 v41, v41
	v_add_f32_e32 v1, 1.0, v1
	v_add_f32_e32 v7, 1.0, v7
	v_add_f32_e32 v42, 1.0, v40
	v_add_f32_e32 v43, 1.0, v41
	v_rcp_f32_e32 v40, v1
	v_rcp_f32_e32 v41, v7
	v_rcp_f32_e32 v42, v42
	v_rcp_f32_e32 v43, v43
	v_pk_mul_f32 v[30:31], v[30:31], v[32:33]
	v_pk_mul_f32 v[28:29], v[28:29], v[34:35]
	v_pk_mul_f32 v[32:33], v[40:41], v[38:39]
	v_pk_mul_f32 v[34:35], v[42:43], v[36:37]
	v_pk_mul_f32 v[30:31], v[30:31], v[32:33]
	v_pk_mul_f32 v[28:29], v[28:29], v[34:35]
	v_cvt_pk_bf16_f32 v30, v30, v31
	v_cvt_pk_bf16_f32 v31, v28, v29
	global_store_dwordx2 v[2:3], v[30:31], off offset:144
	s_waitcnt vmcnt(12)
; __device__ __forceinline__ float bflo(unsigned w) { return __uint_as_float(w << 16); }
; __device__ __forceinline__ float bfhi(unsigned w) { return __uint_as_float(w & 0xffff0000u); }
; __device__ __forceinline__ unsigned pk2(float lo, float hi) { const f32x2 v = {lo, hi}; return __builtin_bit_cast(unsigned, __builtin_convertvector(v, bf16x2_t)); }
; __device__ __forceinline__ float silu(float x) { return x * __builtin_amdgcn_rcpf(1.f + __builtin_amdgcn_exp2f(-1.4426950408889634f * x)); }
; __device__ __forceinline__ void ret_out_item(LAS unsigned char* lds, const bf16* Z, const bf16* AT, const float* gn, bf16* MIXED, int b, int c, const float* lgs) {
;     ...
; #pragma unroll
;     for (int eb = 0; eb < 4; ++eb)
; #pragma unroll
;         for (int rg = 0; rg < 4; ++rg) { const int e0 = 32 * eb + 8 * rg + 4 * hi;
;             const u32x2 gt = *(const u32x2*)(Z + (size_t)row * NZ + ZC_RG + hh * 128 + e0); const f32x4 gg = *(const f32x4*)(gn + hh * 128 + e0);
;             const float y0 = (acc[eb][4 * rg] - mean) * rstd * gg.x * silu(bflo(gt.x)), y1 = (acc[eb][4 * rg + 1] - mean) * rstd * gg.y * silu(bfhi(gt.x));
;             const float y2 = (acc[eb][4 * rg + 2] - mean) * rstd * gg.z * silu(bflo(gt.y)), y3 = (acc[eb][4 * rg + 3] - mean) * rstd * gg.w * silu(bfhi(gt.y));
;             u32x2 w; w.x = pk2(y0, y1); w.y = pk2(y2, y3); *(u32x2*)(MIXED + (size_t)row * 1024 + 512 + hh * 128 + e0) = w; }
	v_mov_b32_e32 v32, v238
	v_mov_b32_e32 v33, v239
	v_mov_b32_e32 v28, v212
	v_mov_b32_e32 v29, v213
	v_mov_b32_e32 v30, v214
	v_mov_b32_e32 v31, v215
	s_nop 0
	v_pk_mul_f32 v[26:27], v[26:27], v[6:7] op_sel_hi:[1,0]
	v_pk_mul_f32 v[24:25], v[24:25], v[6:7] op_sel_hi:[1,0]
	s_waitcnt lgkmcnt(0)
	v_lshlrev_b32_e32 v34, 16, v32
	v_and_b32_e32 v35, 0xffff0000, v32
	v_lshlrev_b32_e32 v32, 16, v33
	v_and_b32_e32 v33, 0xffff0000, v33
	v_mul_f32_e32 v1, 0xbfb8aa3b, v34
	v_mul_f32_e32 v7, 0xbfb8aa3b, v35
	v_mul_f32_e32 v36, 0xbfb8aa3b, v32
	v_mul_f32_e32 v37, 0xbfb8aa3b, v33
	v_exp_f32_e32 v1, v1
	v_exp_f32_e32 v7, v7
	v_exp_f32_e32 v36, v36
	v_exp_f32_e32 v37, v37
	v_add_f32_e32 v1, 1.0, v1
	v_add_f32_e32 v7, 1.0, v7
	v_add_f32_e32 v38, 1.0, v36
	v_add_f32_e32 v39, 1.0, v37
	v_rcp_f32_e32 v36, v1
	v_rcp_f32_e32 v37, v7
	v_rcp_f32_e32 v38, v38
	v_rcp_f32_e32 v39, v39
	v_pk_mul_f32 v[26:27], v[26:27], v[28:29]
	v_pk_mul_f32 v[24:25], v[24:25], v[30:31]
	v_pk_mul_f32 v[28:29], v[36:37], v[34:35]
	v_pk_mul_f32 v[30:31], v[38:39], v[32:33]
	v_pk_mul_f32 v[26:27], v[26:27], v[28:29]
	v_pk_mul_f32 v[24:25], v[24:25], v[30:31]
	v_cvt_pk_bf16_f32 v26, v26, v27
	v_cvt_pk_bf16_f32 v27, v24, v25
	global_store_dwordx2 v[2:3], v[26:27], off offset:160
	s_waitcnt vmcnt(11)
	v_mov_b32_e32 v28, v240
	v_mov_b32_e32 v29, v241
	v_mov_b32_e32 v24, v216
	v_mov_b32_e32 v25, v217
	v_mov_b32_e32 v26, v218
	v_mov_b32_e32 v27, v219
	s_nop 0
	v_pk_mul_f32 v[22:23], v[22:23], v[6:7] op_sel_hi:[1,0]
	v_pk_mul_f32 v[20:21], v[20:21], v[6:7] op_sel_hi:[1,0]
	v_or_b32_e32 v30, 0xc0, v138
	v_mov_b32_e32 v31, v0
	v_lshl_add_u64 v[32:33], v[72:73], 0, s[2:3]
	v_lshl_add_u64 v[30:31], v[32:33], 0, v[30:31]
	s_waitcnt lgkmcnt(0)
	v_lshlrev_b32_e32 v34, 16, v28
	v_and_b32_e32 v35, 0xffff0000, v28
	v_lshlrev_b32_e32 v28, 16, v29
	v_and_b32_e32 v29, 0xffff0000, v29
	v_mul_f32_e32 v1, 0xbfb8aa3b, v34
	v_mul_f32_e32 v7, 0xbfb8aa3b, v35
	v_mul_f32_e32 v36, 0xbfb8aa3b, v28
	v_mul_f32_e32 v37, 0xbfb8aa3b, v29
	v_exp_f32_e32 v1, v1
	v_exp_f32_e32 v7, v7
	v_exp_f32_e32 v36, v36
	v_exp_f32_e32 v37, v37
	v_add_f32_e32 v1, 1.0, v1
	v_add_f32_e32 v7, 1.0, v7
	v_add_f32_e32 v38, 1.0, v36
	v_add_f32_e32 v39, 1.0, v37
	v_rcp_f32_e32 v36, v1
	v_rcp_f32_e32 v37, v7
	v_rcp_f32_e32 v38, v38
	v_rcp_f32_e32 v39, v39
	v_pk_mul_f32 v[22:23], v[22:23], v[24:25]
	v_pk_mul_f32 v[20:21], v[20:21], v[26:27]
	v_pk_mul_f32 v[24:25], v[36:37], v[34:35]
	v_pk_mul_f32 v[26:27], v[38:39], v[28:29]
	v_pk_mul_f32 v[22:23], v[22:23], v[24:25]
	v_pk_mul_f32 v[20:21], v[20:21], v[26:27]
	v_cvt_pk_bf16_f32 v22, v22, v23
	v_cvt_pk_bf16_f32 v23, v20, v21
	global_store_dwordx2 v[2:3], v[22:23], off offset:176
	global_load_dwordx2 v[24:25], v[30:31], off
	s_nop 0
	global_load_dwordx4 v[20:23], v[70:71], off offset:384
	v_pk_mul_f32 v[18:19], v[18:19], v[6:7] op_sel_hi:[1,0]
	v_pk_mul_f32 v[16:17], v[16:17], v[6:7] op_sel_hi:[1,0]
	v_or_b32_e32 v26, 0xd0, v138
	v_mov_b32_e32 v27, v0
	v_lshl_add_u64 v[26:27], v[32:33], 0, v[26:27]
	s_waitcnt vmcnt(0) lgkmcnt(0)
	v_lshlrev_b32_e32 v28, 16, v24
	v_and_b32_e32 v29, 0xffff0000, v24
	v_lshlrev_b32_e32 v24, 16, v25
	v_and_b32_e32 v25, 0xffff0000, v25
	v_mul_f32_e32 v1, 0xbfb8aa3b, v28
	v_mul_f32_e32 v7, 0xbfb8aa3b, v29
	v_mul_f32_e32 v30, 0xbfb8aa3b, v24
	v_mul_f32_e32 v31, 0xbfb8aa3b, v25
	v_exp_f32_e32 v1, v1
	v_exp_f32_e32 v7, v7
	v_exp_f32_e32 v30, v30
	v_exp_f32_e32 v31, v31
	v_add_f32_e32 v1, 1.0, v1
	v_add_f32_e32 v7, 1.0, v7
	v_add_f32_e32 v34, 1.0, v30
	v_add_f32_e32 v35, 1.0, v31
	v_rcp_f32_e32 v30, v1
	v_rcp_f32_e32 v31, v7
	v_rcp_f32_e32 v34, v34
	v_rcp_f32_e32 v35, v35
	v_pk_mul_f32 v[18:19], v[18:19], v[20:21]
	v_pk_mul_f32 v[16:17], v[16:17], v[22:23]
	v_pk_mul_f32 v[20:21], v[30:31], v[28:29]
	v_pk_mul_f32 v[22:23], v[34:35], v[24:25]
	v_pk_mul_f32 v[18:19], v[18:19], v[20:21]
	v_pk_mul_f32 v[16:17], v[16:17], v[22:23]
	v_cvt_pk_bf16_f32 v18, v18, v19
	v_cvt_pk_bf16_f32 v19, v16, v17
	global_store_dwordx2 v[2:3], v[18:19], off offset:192
	global_load_dwordx2 v[20:21], v[26:27], off
	s_nop 0
	global_load_dwordx4 v[16:19], v[70:71], off offset:416
	v_pk_mul_f32 v[14:15], v[14:15], v[6:7] op_sel_hi:[1,0]
	v_pk_mul_f32 v[12:13], v[12:13], v[6:7] op_sel_hi:[1,0]
	v_or_b32_e32 v22, 0xe0, v138
	v_mov_b32_e32 v23, v0
	v_lshl_add_u64 v[22:23], v[32:33], 0, v[22:23]
	s_waitcnt vmcnt(0) lgkmcnt(0)
; __device__ __forceinline__ float bflo(unsigned w) { return __uint_as_float(w << 16); }
; __device__ __forceinline__ float bfhi(unsigned w) { return __uint_as_float(w & 0xffff0000u); }
; __device__ __forceinline__ unsigned pk2(float lo, float hi) { const f32x2 v = {lo, hi}; return __builtin_bit_cast(unsigned, __builtin_convertvector(v, bf16x2_t)); }
; __device__ __forceinline__ float silu(float x) { return x * __builtin_amdgcn_rcpf(1.f + __builtin_amdgcn_exp2f(-1.4426950408889634f * x)); }
; __device__ __forceinline__ void ret_out_item(LAS unsigned char* lds, const bf16* Z, const bf16* AT, const float* gn, bf16* MIXED, int b, int c, const float* lgs) {
;     ...
; #pragma unroll
;     for (int eb = 0; eb < 4; ++eb)
; #pragma unroll
;         for (int rg = 0; rg < 4; ++rg) { const int e0 = 32 * eb + 8 * rg + 4 * hi;
;             const u32x2 gt = *(const u32x2*)(Z + (size_t)row * NZ + ZC_RG + hh * 128 + e0); const f32x4 gg = *(const f32x4*)(gn + hh * 128 + e0);
;             const float y0 = (acc[eb][4 * rg] - mean) * rstd * gg.x * silu(bflo(gt.x)), y1 = (acc[eb][4 * rg + 1] - mean) * rstd * gg.y * silu(bfhi(gt.x));
;             const float y2 = (acc[eb][4 * rg + 2] - mean) * rstd * gg.z * silu(bflo(gt.y)), y3 = (acc[eb][4 * rg + 3] - mean) * rstd * gg.w * silu(bfhi(gt.y));
;             u32x2 w; w.x = pk2(y0, y1); w.y = pk2(y2, y3); *(u32x2*)(MIXED + (size_t)row * 1024 + 512 + hh * 128 + e0) = w; }
	v_lshlrev_b32_e32 v24, 16, v20
	v_and_b32_e32 v25, 0xffff0000, v20
	v_lshlrev_b32_e32 v20, 16, v21
	v_and_b32_e32 v21, 0xffff0000, v21
	v_mul_f32_e32 v1, 0xbfb8aa3b, v24
	v_mul_f32_e32 v7, 0xbfb8aa3b, v25
	v_mul_f32_e32 v26, 0xbfb8aa3b, v20
	v_mul_f32_e32 v27, 0xbfb8aa3b, v21
	v_exp_f32_e32 v1, v1
	v_exp_f32_e32 v7, v7
	v_exp_f32_e32 v26, v26
	v_exp_f32_e32 v27, v27
	v_add_f32_e32 v1, 1.0, v1
	v_add_f32_e32 v7, 1.0, v7
	v_add_f32_e32 v28, 1.0, v26
	v_add_f32_e32 v29, 1.0, v27
	v_rcp_f32_e32 v26, v1
	v_rcp_f32_e32 v27, v7
	v_rcp_f32_e32 v28, v28
	v_rcp_f32_e32 v29, v29
	v_pk_mul_f32 v[14:15], v[14:15], v[16:17]
	v_pk_mul_f32 v[12:13], v[12:13], v[18:19]
	v_pk_mul_f32 v[16:17], v[26:27], v[24:25]
	v_pk_mul_f32 v[18:19], v[28:29], v[20:21]
	v_pk_mul_f32 v[14:15], v[14:15], v[16:17]
	v_pk_mul_f32 v[12:13], v[12:13], v[18:19]
	v_cvt_pk_bf16_f32 v14, v14, v15
	v_cvt_pk_bf16_f32 v15, v12, v13
	global_store_dwordx2 v[2:3], v[14:15], off offset:208
	global_load_dwordx2 v[16:17], v[22:23], off
	s_nop 0
	global_load_dwordx4 v[12:15], v[70:71], off offset:448
	v_pk_mul_f32 v[10:11], v[10:11], v[6:7] op_sel_hi:[1,0]
	v_pk_mul_f32 v[8:9], v[8:9], v[6:7] op_sel_hi:[1,0]
	v_or_b32_e32 v18, 0xf0, v138
	v_mov_b32_e32 v19, v0
	v_lshl_add_u64 v[18:19], v[32:33], 0, v[18:19]
	s_waitcnt vmcnt(0) lgkmcnt(0)
	v_lshlrev_b32_e32 v20, 16, v16
	v_and_b32_e32 v21, 0xffff0000, v16
	v_lshlrev_b32_e32 v16, 16, v17
	v_and_b32_e32 v17, 0xffff0000, v17
	v_mul_f32_e32 v1, 0xbfb8aa3b, v20
	v_mul_f32_e32 v7, 0xbfb8aa3b, v21
	v_mul_f32_e32 v22, 0xbfb8aa3b, v16
	v_mul_f32_e32 v23, 0xbfb8aa3b, v17
	v_exp_f32_e32 v1, v1
	v_exp_f32_e32 v7, v7
	v_exp_f32_e32 v22, v22
	v_exp_f32_e32 v23, v23
	v_add_f32_e32 v1, 1.0, v1
	v_add_f32_e32 v7, 1.0, v7
	v_add_f32_e32 v24, 1.0, v22
	v_add_f32_e32 v25, 1.0, v23
	v_rcp_f32_e32 v22, v1
	v_rcp_f32_e32 v23, v7
	v_rcp_f32_e32 v24, v24
	v_rcp_f32_e32 v25, v25
	v_pk_mul_f32 v[10:11], v[10:11], v[12:13]
	v_pk_mul_f32 v[8:9], v[8:9], v[14:15]
	v_pk_mul_f32 v[12:13], v[22:23], v[20:21]
	v_pk_mul_f32 v[14:15], v[24:25], v[16:17]
	v_pk_mul_f32 v[10:11], v[10:11], v[12:13]
	v_pk_mul_f32 v[8:9], v[8:9], v[14:15]
	v_cvt_pk_bf16_f32 v10, v10, v11
	v_cvt_pk_bf16_f32 v11, v8, v9
	global_store_dwordx2 v[2:3], v[10:11], off offset:224
	global_load_dwordx2 v[12:13], v[18:19], off
	s_nop 0
	global_load_dwordx4 v[8:11], v[70:71], off offset:480
	v_pk_mul_f32 v[4:5], v[4:5], v[6:7] op_sel_hi:[1,0]
	v_pk_mul_f32 v[6:7], v[48:49], v[6:7] op_sel_hi:[1,0]
	s_waitcnt vmcnt(0) lgkmcnt(0)
	v_lshlrev_b32_e32 v14, 16, v12
	v_and_b32_e32 v15, 0xffff0000, v12
	v_lshlrev_b32_e32 v12, 16, v13
	v_and_b32_e32 v13, 0xffff0000, v13
	v_mul_f32_e32 v1, 0xbfb8aa3b, v14
	v_mul_f32_e32 v16, 0xbfb8aa3b, v15
	v_mul_f32_e32 v17, 0xbfb8aa3b, v12
	v_mul_f32_e32 v18, 0xbfb8aa3b, v13
	v_exp_f32_e32 v1, v1
	v_exp_f32_e32 v16, v16
	v_exp_f32_e32 v17, v17
	v_exp_f32_e32 v18, v18
	v_add_f32_e32 v1, 1.0, v1
	v_add_f32_e32 v19, 1.0, v16
	v_add_f32_e32 v20, 1.0, v17
	v_add_f32_e32 v21, 1.0, v18
	v_rcp_f32_e32 v16, v1
	v_rcp_f32_e32 v17, v19
	v_rcp_f32_e32 v18, v20
	v_rcp_f32_e32 v19, v21
	v_pk_mul_f32 v[4:5], v[4:5], v[8:9]
	v_pk_mul_f32 v[6:7], v[6:7], v[10:11]
	v_pk_mul_f32 v[8:9], v[16:17], v[14:15]
	v_pk_mul_f32 v[10:11], v[18:19], v[12:13]
	v_pk_mul_f32 v[4:5], v[4:5], v[8:9]
	v_pk_mul_f32 v[6:7], v[6:7], v[10:11]
	v_cvt_pk_bf16_f32 v4, v4, v5
	v_cvt_pk_bf16_f32 v5, v6, v7
	global_store_dwordx2 v[2:3], v[4:5], off offset:240
	s_waitcnt lgkmcnt(0)
	s_barrier
